# mode3 out-proj epilogue: residual loads batched 16 deep instead of 32 serialized round trips
# speedup vs baseline: 1.0050x; 1.0050x over previous
;     ...
;             for (int n = 0; n < 2; ++n) {
;               const int nc = brow + ai * 128 + wr * 64 + m * 16 + fq * 4;
;               const int tok = bcol + bj * 128 + wc * 32 + n * 16 + fr;
;               const int ncw = brow + ai * 128 + wr * 64 + ((m & ~1) + (fq & 1)) * 16 + (fq & ~1) * 4;
;     ...
;               f32x4 v = acc[ai][bj][m][n];
;               if (MODE == 0) {
;                 if (tn == 52) {
;                   if (ai == 0) *(float4*)((float*)(ws + OFF_DTR) + (size_t)tok * 128 + (nc - 13312)) = make_float4(v[0], v[1], v[2], v[3]);
;                 } else {
;                   u16* dst; int ld, c0;
;                   if (tn < 16) { dst = (u16*)(ws + OFF_Z); ld = 4096; c0 = 0; }
;                   else if (tn < 40) { dst = (u16*)(ws + OFF_RA); ld = 6144; c0 = 4096; }
;                   else if (tn < 48) { dst = (u16*)(ws + OFF_Q); ld = 2048; c0 = 10240; }
;                   else if (tn < 50) { dst = (u16*)(ws + OFF_K); ld = 512; c0 = 12288; }
;                   else { dst = (u16*)(ws + OFF_V); ld = 512; c0 = 12800; }
;                   uint2 o; o.x = pk2(v[0], v[1]); o.y = pk2(v[2], v[3]);
;                   WIDE_STORE(dst, ld, c0, o);
;                 }
;               } else if (MODE == 1) {
;                 uint2 o; o.x = pk2(sigmoidf_(v[0]), sigmoidf_(v[1])); o.y = pk2(sigmoidf_(v[2]), sigmoidf_(v[3]));
;                 WIDE_STORE((u16*)outp, 4096, 0, o);
;               } else if (MODE == 2) {
;                 const u16* gate = (const u16*)outp;
;                 uint2 ga = *(const uint2*)(gate + (size_t)tok * 4096 + nc);
;                 uint2 p1; p1.x = pk2(v[0] * bflo(ga.x), v[1] * bfhi(ga.x)); p1.y = pk2(v[2] * bflo(ga.y), v[3] * bfhi(ga.y));
;                 *(uint2*)((u16*)(ws + OFF_YB) + (size_t)tok * DM + nc) = p1;
;               } else if (MODE == 6) {
;                 const u16* gate = (const u16*)outp;
;                 uint2 gb = *(const uint2*)(gate + (size_t)tok * 4096 + 2048 + nc);
;                 const uint2 p1 = *(const uint2*)((const u16*)(ws + OFF_YB) + (size_t)tok * DM + nc);
;                 uint2 o;
;                 o.x = pk2(bflo(p1.x) + v[0] * bflo(gb.x), bfhi(p1.x) + v[1] * bfhi(gb.x));
;                 o.y = pk2(bflo(p1.y) + v[2] * bflo(gb.y), bfhi(p1.y) + v[3] * bfhi(gb.y));
;                 WIDE_STORE((u16*)(ws + OFF_RB + 128 * MiB), DM, 0, o);
;               } else if (MODE == 3) {
.LBB0_895:
	v_readlane_b32 s2, v245, 25
	v_readlane_b32 s3, v245, 26
	s_add_i32 s0, s0, s49
	v_and_b32_e32 v192, 15, v146
	v_or_b32_e32 v192, s54, v192
	v_or_b32_e32 v192, s29, v192
	v_lshrrev_b32_e32 v193, 2, v146
	v_and_b32_e32 v194, -4, v193
	v_add_u32_e32 v194, s0, v194
	v_and_b32_e32 v193, -8, v193
	v_and_b32_e32 v195, 16, v146
	v_add3_u32 v193, v193, v195, s0
	v_lshlrev_b32_e32 v195, 13, v192
	v_lshl_add_u32 v138, v194, 2, v195
	v_add_u32_e32 v139, 0x20000, v138
	v_add_u32_e32 v140, 0x100000, v138
	v_add_u32_e32 v141, 0x120000, v138
	v_lshlrev_b32_e32 v195, 12, v192
	v_lshl_add_u32 v142, v193, 1, v195
	v_add_u32_e32 v143, 0x10000, v142
	v_add_u32_e32 v190, 0x80000, v142
	v_add_u32_e32 v191, 0x90000, v142
	global_load_dwordx4 v[210:213], v138, s[6:7] offset:0 nt
	global_load_dwordx4 v[214:217], v138, s[6:7] offset:64 nt
	global_load_dwordx4 v[218:221], v138, s[6:7] offset:128 nt
	global_load_dwordx4 v[222:225], v138, s[6:7] offset:192 nt
	global_load_dwordx4 v[226:229], v139, s[6:7] offset:0 nt
	global_load_dwordx4 v[230:233], v139, s[6:7] offset:64 nt
	global_load_dwordx4 v[234:237], v139, s[6:7] offset:128 nt
	global_load_dwordx4 v[238:241], v139, s[6:7] offset:192 nt
	global_load_dwordx4 v[168:171], v140, s[6:7] offset:0 nt
	global_load_dwordx4 v[172:175], v140, s[6:7] offset:64 nt
	global_load_dwordx4 v[176:179], v140, s[6:7] offset:128 nt
	global_load_dwordx4 v[180:183], v140, s[6:7] offset:192 nt
	global_load_dwordx4 v[152:155], v141, s[6:7] offset:0 nt
	global_load_dwordx4 v[156:159], v141, s[6:7] offset:64 nt
	global_load_dwordx4 v[160:163], v141, s[6:7] offset:128 nt
	global_load_dwordx4 v[134:137], v141, s[6:7] offset:192 nt
	s_waitcnt vmcnt(15)
	v_pk_add_f32 v[124:125], v[124:125], v[210:211]
	v_pk_add_f32 v[126:127], v[126:127], v[212:213]
	global_load_dwordx4 v[210:213], v138, s[6:7] offset:512 nt
	s_waitcnt vmcnt(15)
	v_pk_add_f32 v[116:117], v[116:117], v[214:215]
	v_pk_add_f32 v[118:119], v[118:119], v[216:217]
	global_load_dwordx4 v[214:217], v138, s[6:7] offset:576 nt
	s_waitcnt vmcnt(15)
	v_pk_add_f32 v[108:109], v[108:109], v[218:219]
	v_pk_add_f32 v[110:111], v[110:111], v[220:221]
	global_load_dwordx4 v[218:221], v138, s[6:7] offset:640 nt
	s_waitcnt vmcnt(15)
	v_pk_add_f32 v[100:101], v[100:101], v[222:223]
	v_pk_add_f32 v[102:103], v[102:103], v[224:225]
	global_load_dwordx4 v[222:225], v138, s[6:7] offset:704 nt
	s_waitcnt vmcnt(15)
	v_pk_add_f32 v[120:121], v[120:121], v[226:227]
	v_pk_add_f32 v[122:123], v[122:123], v[228:229]
	global_load_dwordx4 v[226:229], v139, s[6:7] offset:512 nt
	s_waitcnt vmcnt(15)
	v_pk_add_f32 v[112:113], v[112:113], v[230:231]
	v_pk_add_f32 v[114:115], v[114:115], v[232:233]
	global_load_dwordx4 v[230:233], v139, s[6:7] offset:576 nt
	s_waitcnt vmcnt(15)
	v_pk_add_f32 v[104:105], v[104:105], v[234:235]
	v_pk_add_f32 v[106:107], v[106:107], v[236:237]
	global_load_dwordx4 v[234:237], v139, s[6:7] offset:640 nt
	s_waitcnt vmcnt(15)
	v_pk_add_f32 v[96:97], v[96:97], v[238:239]
	v_pk_add_f32 v[98:99], v[98:99], v[240:241]
	global_load_dwordx4 v[238:241], v139, s[6:7] offset:704 nt
	s_waitcnt vmcnt(15)
	v_pk_add_f32 v[92:93], v[92:93], v[168:169]
	v_pk_add_f32 v[94:95], v[94:95], v[170:171]
	global_load_dwordx4 v[168:171], v140, s[6:7] offset:512 nt
	s_waitcnt vmcnt(15)
	v_pk_add_f32 v[84:85], v[84:85], v[172:173]
	v_pk_add_f32 v[86:87], v[86:87], v[174:175]
	global_load_dwordx4 v[172:175], v140, s[6:7] offset:576 nt
	s_waitcnt vmcnt(15)
	v_pk_add_f32 v[76:77], v[76:77], v[176:177]
	v_pk_add_f32 v[78:79], v[78:79], v[178:179]
	global_load_dwordx4 v[176:179], v140, s[6:7] offset:640 nt
	s_waitcnt vmcnt(15)
	v_pk_add_f32 v[68:69], v[68:69], v[180:181]
	v_pk_add_f32 v[70:71], v[70:71], v[182:183]
	global_load_dwordx4 v[180:183], v140, s[6:7] offset:704 nt
	s_waitcnt vmcnt(15)
	v_pk_add_f32 v[88:89], v[88:89], v[152:153]
	v_pk_add_f32 v[90:91], v[90:91], v[154:155]
	global_load_dwordx4 v[152:155], v141, s[6:7] offset:512 nt
	s_waitcnt vmcnt(15)
	v_pk_add_f32 v[80:81], v[80:81], v[156:157]
	v_pk_add_f32 v[82:83], v[82:83], v[158:159]
	global_load_dwordx4 v[156:159], v141, s[6:7] offset:576 nt
	s_waitcnt vmcnt(15)
	v_pk_add_f32 v[72:73], v[72:73], v[160:161]
	v_pk_add_f32 v[74:75], v[74:75], v[162:163]
	global_load_dwordx4 v[160:163], v141, s[6:7] offset:640 nt
	s_waitcnt vmcnt(15)
;     ...
;             for (int n = 0; n < 2; ++n) {
;               const int nc = brow + ai * 128 + wr * 64 + m * 16 + fq * 4;
;               const int tok = bcol + bj * 128 + wc * 32 + n * 16 + fr;
;               const int ncw = brow + ai * 128 + wr * 64 + ((m & ~1) + (fq & 1)) * 16 + (fq & ~1) * 4;
;     ...
;               f32x4 v = acc[ai][bj][m][n];
;               if (MODE == 0) {
;                 if (tn == 52) {
;                   if (ai == 0) *(float4*)((float*)(ws + OFF_DTR) + (size_t)tok * 128 + (nc - 13312)) = make_float4(v[0], v[1], v[2], v[3]);
;                 } else {
;                   u16* dst; int ld, c0;
;                   if (tn < 16) { dst = (u16*)(ws + OFF_Z); ld = 4096; c0 = 0; }
;                   else if (tn < 40) { dst = (u16*)(ws + OFF_RA); ld = 6144; c0 = 4096; }
;                   else if (tn < 48) { dst = (u16*)(ws + OFF_Q); ld = 2048; c0 = 10240; }
;                   else if (tn < 50) { dst = (u16*)(ws + OFF_K); ld = 512; c0 = 12288; }
;                   else { dst = (u16*)(ws + OFF_V); ld = 512; c0 = 12800; }
;                   uint2 o; o.x = pk2(v[0], v[1]); o.y = pk2(v[2], v[3]);
;                   WIDE_STORE(dst, ld, c0, o);
;                 }
;               } else if (MODE == 1) {
;                 uint2 o; o.x = pk2(sigmoidf_(v[0]), sigmoidf_(v[1])); o.y = pk2(sigmoidf_(v[2]), sigmoidf_(v[3]));
;                 WIDE_STORE((u16*)outp, 4096, 0, o);
;               } else if (MODE == 2) {
;                 const u16* gate = (const u16*)outp;
;                 uint2 ga = *(const uint2*)(gate + (size_t)tok * 4096 + nc);
;                 uint2 p1; p1.x = pk2(v[0] * bflo(ga.x), v[1] * bfhi(ga.x)); p1.y = pk2(v[2] * bflo(ga.y), v[3] * bfhi(ga.y));
;                 *(uint2*)((u16*)(ws + OFF_YB) + (size_t)tok * DM + nc) = p1;
;               } else if (MODE == 6) {
;                 const u16* gate = (const u16*)outp;
;                 uint2 gb = *(const uint2*)(gate + (size_t)tok * 4096 + 2048 + nc);
;                 const uint2 p1 = *(const uint2*)((const u16*)(ws + OFF_YB) + (size_t)tok * DM + nc);
;                 uint2 o;
;                 o.x = pk2(bflo(p1.x) + v[0] * bflo(gb.x), bfhi(p1.x) + v[1] * bfhi(gb.x));
;                 o.y = pk2(bflo(p1.y) + v[2] * bflo(gb.y), bfhi(p1.y) + v[3] * bfhi(gb.y));
;                 WIDE_STORE((u16*)(ws + OFF_RB + 128 * MiB), DM, 0, o);
;               } else if (MODE == 3) {
	v_pk_add_f32 v[64:65], v[64:65], v[134:135]
	v_pk_add_f32 v[66:67], v[66:67], v[136:137]
	global_load_dwordx4 v[134:137], v141, s[6:7] offset:704 nt
	v_cvt_pk_bf16_f32 v124, v124, v125
	v_cvt_pk_bf16_f32 v125, v126, v127
	v_cvt_pk_bf16_f32 v126, v116, v117
	v_cvt_pk_bf16_f32 v127, v118, v119
	v_cvt_pk_bf16_f32 v108, v108, v109
	v_cvt_pk_bf16_f32 v109, v110, v111
	v_cvt_pk_bf16_f32 v110, v100, v101
	v_cvt_pk_bf16_f32 v111, v102, v103
	s_nop 1
	v_permlane16_swap_b32_e32 v124, v126
	v_permlane16_swap_b32_e32 v125, v127
	v_permlane16_swap_b32_e32 v108, v110
	v_permlane16_swap_b32_e32 v109, v111
	global_store_dwordx4 v142, v[124:127], s[2:3] offset:0
	global_store_dwordx4 v142, v[108:111], s[2:3] offset:64
	v_cvt_pk_bf16_f32 v120, v120, v121
	v_cvt_pk_bf16_f32 v121, v122, v123
	v_cvt_pk_bf16_f32 v122, v112, v113
	v_cvt_pk_bf16_f32 v123, v114, v115
	v_cvt_pk_bf16_f32 v104, v104, v105
	v_cvt_pk_bf16_f32 v105, v106, v107
	v_cvt_pk_bf16_f32 v106, v96, v97
	v_cvt_pk_bf16_f32 v107, v98, v99
	s_nop 1
	v_permlane16_swap_b32_e32 v120, v122
	v_permlane16_swap_b32_e32 v121, v123
	v_permlane16_swap_b32_e32 v104, v106
	v_permlane16_swap_b32_e32 v105, v107
	global_store_dwordx4 v143, v[120:123], s[2:3] offset:0
	global_store_dwordx4 v143, v[104:107], s[2:3] offset:64
	v_cvt_pk_bf16_f32 v92, v92, v93
	v_cvt_pk_bf16_f32 v93, v94, v95
	v_cvt_pk_bf16_f32 v94, v84, v85
	v_cvt_pk_bf16_f32 v95, v86, v87
	v_cvt_pk_bf16_f32 v76, v76, v77
	v_cvt_pk_bf16_f32 v77, v78, v79
	v_cvt_pk_bf16_f32 v78, v68, v69
	v_cvt_pk_bf16_f32 v79, v70, v71
	s_nop 1
	v_permlane16_swap_b32_e32 v92, v94
	v_permlane16_swap_b32_e32 v93, v95
	v_permlane16_swap_b32_e32 v76, v78
	v_permlane16_swap_b32_e32 v77, v79
	global_store_dwordx4 v190, v[92:95], s[2:3] offset:0
	global_store_dwordx4 v190, v[76:79], s[2:3] offset:64
	v_cvt_pk_bf16_f32 v88, v88, v89
	v_cvt_pk_bf16_f32 v89, v90, v91
	v_cvt_pk_bf16_f32 v90, v80, v81
	v_cvt_pk_bf16_f32 v91, v82, v83
	v_cvt_pk_bf16_f32 v72, v72, v73
	v_cvt_pk_bf16_f32 v73, v74, v75
	v_cvt_pk_bf16_f32 v74, v64, v65
	v_cvt_pk_bf16_f32 v75, v66, v67
	s_nop 1
	v_permlane16_swap_b32_e32 v88, v90
	v_permlane16_swap_b32_e32 v89, v91
	v_permlane16_swap_b32_e32 v72, v74
	v_permlane16_swap_b32_e32 v73, v75
	global_store_dwordx4 v191, v[88:91], s[2:3] offset:0
	global_store_dwordx4 v191, v[72:75], s[2:3] offset:64
	s_waitcnt vmcnt(23)
	v_pk_add_f32 v[60:61], v[60:61], v[210:211]
	v_pk_add_f32 v[62:63], v[62:63], v[212:213]
	s_waitcnt vmcnt(22)
	v_pk_add_f32 v[52:53], v[52:53], v[214:215]
	v_pk_add_f32 v[54:55], v[54:55], v[216:217]
	s_waitcnt vmcnt(21)
	v_pk_add_f32 v[44:45], v[44:45], v[218:219]
	v_pk_add_f32 v[46:47], v[46:47], v[220:221]
	s_waitcnt vmcnt(20)
	v_pk_add_f32 v[36:37], v[36:37], v[222:223]
	v_pk_add_f32 v[38:39], v[38:39], v[224:225]
	s_waitcnt vmcnt(19)
	v_pk_add_f32 v[56:57], v[56:57], v[226:227]
	v_pk_add_f32 v[58:59], v[58:59], v[228:229]
	s_waitcnt vmcnt(18)
	v_pk_add_f32 v[48:49], v[48:49], v[230:231]
	v_pk_add_f32 v[50:51], v[50:51], v[232:233]
	s_waitcnt vmcnt(17)
	v_pk_add_f32 v[40:41], v[40:41], v[234:235]
	v_pk_add_f32 v[42:43], v[42:43], v[236:237]
	s_waitcnt vmcnt(16)
	v_pk_add_f32 v[32:33], v[32:33], v[238:239]
	v_pk_add_f32 v[34:35], v[34:35], v[240:241]
	s_waitcnt vmcnt(15)
	v_pk_add_f32 v[28:29], v[28:29], v[168:169]
	v_pk_add_f32 v[30:31], v[30:31], v[170:171]
	s_waitcnt vmcnt(14)
	v_pk_add_f32 v[20:21], v[20:21], v[172:173]
	v_pk_add_f32 v[22:23], v[22:23], v[174:175]
	s_waitcnt vmcnt(13)
	v_pk_add_f32 v[12:13], v[12:13], v[176:177]
	v_pk_add_f32 v[14:15], v[14:15], v[178:179]
	s_waitcnt vmcnt(12)
	v_pk_add_f32 v[4:5], v[4:5], v[180:181]
	v_pk_add_f32 v[6:7], v[6:7], v[182:183]
	s_waitcnt vmcnt(11)
	v_pk_add_f32 v[24:25], v[24:25], v[152:153]
	v_pk_add_f32 v[26:27], v[26:27], v[154:155]
	s_waitcnt vmcnt(10)
	v_pk_add_f32 v[16:17], v[16:17], v[156:157]
	v_pk_add_f32 v[18:19], v[18:19], v[158:159]
	s_waitcnt vmcnt(9)
	v_pk_add_f32 v[8:9], v[8:9], v[160:161]
	v_pk_add_f32 v[10:11], v[10:11], v[162:163]
	s_waitcnt vmcnt(8)
	v_pk_add_f32 v[0:1], v[0:1], v[134:135]
	v_pk_add_f32 v[2:3], v[2:3], v[136:137]
	v_cvt_pk_bf16_f32 v60, v60, v61
	v_cvt_pk_bf16_f32 v61, v62, v63
	v_cvt_pk_bf16_f32 v62, v52, v53
	v_cvt_pk_bf16_f32 v63, v54, v55
	v_cvt_pk_bf16_f32 v44, v44, v45
	v_cvt_pk_bf16_f32 v45, v46, v47
	v_cvt_pk_bf16_f32 v46, v36, v37
	v_cvt_pk_bf16_f32 v47, v38, v39
	s_nop 1
	v_permlane16_swap_b32_e32 v60, v62
	v_permlane16_swap_b32_e32 v61, v63
	v_permlane16_swap_b32_e32 v44, v46
	v_permlane16_swap_b32_e32 v45, v47
	global_store_dwordx4 v142, v[60:63], s[2:3] offset:256
	global_store_dwordx4 v142, v[44:47], s[2:3] offset:320
	v_cvt_pk_bf16_f32 v56, v56, v57
	v_cvt_pk_bf16_f32 v57, v58, v59
	v_cvt_pk_bf16_f32 v58, v48, v49
	v_cvt_pk_bf16_f32 v59, v50, v51
	v_cvt_pk_bf16_f32 v40, v40, v41
	v_cvt_pk_bf16_f32 v41, v42, v43
	v_cvt_pk_bf16_f32 v42, v32, v33
	v_cvt_pk_bf16_f32 v43, v34, v35
	s_nop 1
	v_permlane16_swap_b32_e32 v56, v58
	v_permlane16_swap_b32_e32 v57, v59
	v_permlane16_swap_b32_e32 v40, v42
	v_permlane16_swap_b32_e32 v41, v43
	global_store_dwordx4 v143, v[56:59], s[2:3] offset:256
	global_store_dwordx4 v143, v[40:43], s[2:3] offset:320
	v_cvt_pk_bf16_f32 v28, v28, v29
	v_cvt_pk_bf16_f32 v29, v30, v31
	v_cvt_pk_bf16_f32 v30, v20, v21
	v_cvt_pk_bf16_f32 v31, v22, v23
	v_cvt_pk_bf16_f32 v12, v12, v13
	v_cvt_pk_bf16_f32 v13, v14, v15
	v_cvt_pk_bf16_f32 v14, v4, v5
	v_cvt_pk_bf16_f32 v15, v6, v7
	s_nop 1
	v_permlane16_swap_b32_e32 v28, v30
	v_permlane16_swap_b32_e32 v29, v31
	v_permlane16_swap_b32_e32 v12, v14
	v_permlane16_swap_b32_e32 v13, v15
	global_store_dwordx4 v190, v[28:31], s[2:3] offset:256
	global_store_dwordx4 v190, v[12:15], s[2:3] offset:320
	v_cvt_pk_bf16_f32 v24, v24, v25
	v_cvt_pk_bf16_f32 v25, v26, v27
	v_cvt_pk_bf16_f32 v26, v16, v17
	v_cvt_pk_bf16_f32 v27, v18, v19
	v_cvt_pk_bf16_f32 v8, v8, v9
	v_cvt_pk_bf16_f32 v9, v10, v11
	v_cvt_pk_bf16_f32 v10, v0, v1
	v_cvt_pk_bf16_f32 v11, v2, v3
	s_nop 1
	v_permlane16_swap_b32_e32 v24, v26
	v_permlane16_swap_b32_e32 v25, v27
	v_permlane16_swap_b32_e32 v8, v10
	v_permlane16_swap_b32_e32 v9, v11
	global_store_dwordx4 v191, v[24:27], s[2:3] offset:256
	global_store_dwordx4 v191, v[8:11], s[2:3] offset:320
	s_and_b64 s[0:1], s[56:57], s[10:11]
	s_andn2_b64 vcc, exec, s[0:1]
	s_waitcnt vmcnt(0)
	s_cbranch_vccnz .LBB0_886
	s_barrier
	s_branch .LBB0_886
